# attention K/V prefetch uses running 32-bit offsets on the uniform base; V staging loads cover 16 key rows x 64 B per instruction (fewer cache lines per load), same LDS image
# speedup vs baseline: 1.0120x; 1.0096x over previous
; __device__ void attn_item(const Params& p, int s_idx, char* smem) {
;     ...
;     auto gload = [&](int kt, KV& st) {
; #pragma unroll
;         for (int i = 0; i < 2; ++i) {
;             const int c = tid + 256 * i, key = c >> 3, dc = c & 7;
;             const bf16_t* src = projb + (size_t)(kt * 64 + key) * NIN + h * 64 + dc * 8;
;             st.rk[i] = *(const u32x4*)(src + 512);
;             const int keyv = c & 63, dcv = c >> 6;
;             st.rv[i] = *(const u32x4*)(projb + (size_t)(kt * 64 + keyv) * NIN + 1024 + h * 64 + dcv * 8);
;         }
;         st.rkb = p.kb[(size_t)bh * S + kt * 64 + (tid & 63)];
;     };
;     auto sstore = [&](int buf, const KV& st) {
;         bf16_t* sK = (bf16_t*)(smem + buf * ATT_BUF); bf16_t* sVt = sK + 64 * 72; float* sKb = (float*)(smem + buf * ATT_BUF + 18432);
; #pragma unroll
;         for (int i = 0; i < 2; ++i) {
;             const int c = tid + 256 * i, key = c >> 3, dc = c & 7;
;             *(u32x4*)(sK + key * 72 + dc * 8) = st.rk[i];
;             const unsigned w0 = st.rv[i].x, w1 = st.rv[i].y, w2 = st.rv[i].z, w3 = st.rv[i].w;
;             bf16_t* d = sVt + ((c >> 6) * 8) * 72 + (c & 63);
;             d[0 * 72] = (bf16_t)(w0 & 0xffffu); d[1 * 72] = (bf16_t)(w0 >> 16);
;             d[2 * 72] = (bf16_t)(w1 & 0xffffu); d[3 * 72] = (bf16_t)(w1 >> 16);
;             d[4 * 72] = (bf16_t)(w2 & 0xffffu); d[5 * 72] = (bf16_t)(w2 >> 16);
;             d[6 * 72] = (bf16_t)(w3 & 0xffffu); d[7 * 72] = (bf16_t)(w3 >> 16);
;         }
.LBB0_107:
	s_ashr_i32 s12, s15, 5
	s_lshl_b32 s13, s15, 10
	s_sub_i32 s14, 63, s12
	v_mov_b32_e32 v3, v126
	s_and_b32 s13, s13, 0x6000
	s_and_b32 s18, s15, 31
	s_lshl_b32 s12, s14, 7
	v_ashrrev_i32_e32 v143, 6, v3
	s_mul_i32 s16, s13, 0x1410
	v_lshlrev_b32_e32 v96, 5, v143
	s_add_u32 s34, s90, s16
	v_and_b32_e32 v2, 31, v3
	v_add_u32_e32 v144, s12, v96
	s_addc_u32 s35, s91, 0
	s_lshl_b32 s15, s15, 6
	v_or_b32_e32 v98, v144, v2
	s_waitcnt lgkmcnt(0)
	v_mov_b64_e32 v[0:1], s[34:35]
	s_and_b32 s15, s15, 0x1c0
	v_bfe_u32 v4, v3, 5, 1
	v_mad_i64_i32 v[6:7], s[16:17], v98, s29, v[0:1]
	s_lshl_b32 s22, s15, 1
	s_mov_b32 s23, s21
	v_lshl_add_u64 v[6:7], v[6:7], 0, s[22:23]
	v_lshlrev_b32_e32 v112, 4, v4
	v_lshl_add_u64 v[6:7], v[6:7], 0, v[112:113]
	v_ashrrev_i32_e32 v145, 3, v3
	v_lshlrev_b32_e32 v5, 3, v3
	global_load_dwordx4 v[64:67], v[6:7], off
	global_load_dwordx4 v[68:71], v[6:7], off offset:32
	global_load_dwordx4 v[72:75], v[6:7], off offset:64
	global_load_dwordx4 v[76:79], v[6:7], off offset:96
	v_readlane_b32 s98, v165, 2
	v_readlane_b32 s99, v165, 3
	v_readlane_b32 s32, v167, 36
	v_and_b32_e32 v32, 7, v130
	v_bfe_u32 v33, v130, 3, 1
	v_lshlrev_b32_e32 v32, 7, v32
	s_mul_i32 s32, s32, 0xc00
	v_lshl_or_b32 v32, v33, 10, v32
	v_mov_b32_e32 v33, s18
	s_add_i32 s32, s32, 32
	v_and_b32_e32 v33, 7, v33
	v_add_u32_e32 v32, s32, v32
	v_lshl_add_u32 v32, v33, 2, v32
	global_load_dword v34, v32, s[98:99] sc0 sc1
	s_lshl_b32 s32, s18, 15
	v_lshlrev_b32_e32 v35, 8, v130
	v_add_u32_e32 v35, s32, v35
	v_add_u32_e32 v38, 0x4000, v35
	s_lshl_b32 s32, s14, 9
	v_add_u32_e32 v39, s32, v35
	v_lshlrev_b32_e32 v33, 8, v130
	v_sub_u32_e32 v39, v39, v33
	v_readlane_b32 s98, v165, 40
	v_readlane_b32 s99, v165, 41
	s_nop 4
	s_nop 0
	global_load_dword v36, v35, s[98:99] offset:252
	global_load_dword v37, v38, s[98:99] offset:252
	global_load_dword v39, v39, s[98:99]
	s_waitcnt vmcnt(3)
	v_max_u32_dpp v34, v34, v34 quad_perm:[1,0,3,2] row_mask:0xf bank_mask:0xf
	s_nop 1
	v_max_u32_dpp v34, v34, v34 quad_perm:[2,3,0,1] row_mask:0xf bank_mask:0xf
	s_nop 1
	v_max_u32_dpp v34, v34, v34 row_half_mirror row_mask:0xf bank_mask:0xf
	s_waitcnt vmcnt(0)
	s_nop 0
	v_readlane_b32 s98, v34, 0
	v_readlane_b32 s99, v34, 8
	v_mov_b32_e32 v41, 0xbebae186
	s_nop 0
	v_mov_b32_e32 v40, s98
	v_mul_f32_e32 v40, s99, v40
	v_sqrt_f32_e32 v40, v40
	s_nop 0
	v_fma_f32 v40, v40, v41, v39
	v_add_f32_e32 v40, 0xc31b0000, v40
	v_cmp_lt_f32_e32 vcc, v36, v40
	s_bcnt1_i32_b64 s32, vcc
	v_cmp_lt_f32_e32 vcc, v37, v40
	s_bcnt1_i32_b64 s98, vcc
	s_add_i32 s32, s32, s98
	s_lshl_b32 s98, s14, 1
	s_min_i32 s32, s32, s98
	s_and_b32 s32, s32, -2
	s_lshl_b32 s98, s32, 6
	s_lshl_b32 s99, s14, 7
	s_add_i32 s99, s99, 64
	s_mul_i32 s99, s99, 0x1410
	s_add_u32 s34, s34, s99
	s_addc_u32 s35, s35, 0
	s_lshl_b32 s99, s14, 1
	s_add_i32 s99, s99, 1
	s_sub_i32 s99, s99, s32
	s_lshl_b32 s99, s99, 6
	v_subrev_u32_e32 v98, s98, v98
	v_subrev_u32_e32 v144, s98, v144
	v_mov_b64_e32 v[0:1], s[34:35]
	v_mad_i64_i32 v[6:7], s[16:17], v145, s29, v[0:1]
	v_and_b32_e32 v5, 56, v5
	v_lshl_add_u64 v[6:7], v[6:7], 0, s[22:23]
	v_lshlrev_b32_e32 v112, 1, v5
	v_lshl_add_u64 v[6:7], v[6:7], 0, v[112:113]
	global_load_dwordx4 v[6:9], v[6:7], off offset:1024
	v_add_u32_e32 v5, 0x100, v3
	v_and_b32_e32 v114, 63, v3
	v_ashrrev_i32_e32 v146, 3, v5
	v_lshrrev_b32_e32 v135, 6, v3
	v_and_b32_e32 v10, 15, v3
	v_lshl_or_b32 v135, v135, 4, v10
	v_mul_u32_u24_e32 v10, 0x1410, v135
	v_mov_b32_e32 v11, v113
	v_mad_i64_i32 v[0:1], s[16:17], v146, s29, v[0:1]
	v_readlane_b32 s48, v165, 26
	v_lshl_add_u64 v[10:11], s[34:35], 0, v[10:11]
	v_bfe_u32 v100, v3, 4, 2
	v_lshlrev_b32_e32 v100, 3, v100
	v_lshl_add_u64 v[0:1], v[0:1], 0, s[22:23]
	v_add_u32_e32 v102, 32, v100
	s_lshl_b32 s15, s18, 15
	v_readlane_b32 s62, v165, 40
	v_lshl_add_u64 v[14:15], v[10:11], 0, s[22:23]
	v_ashrrev_i32_e32 v101, 31, v100
	v_lshl_add_u64 v[0:1], v[0:1], 0, v[112:113]
	v_ashrrev_i32_e32 v103, 31, v102
	v_readlane_b32 s63, v165, 41
	s_add_u32 s16, s62, s15
	v_lshl_add_u64 v[16:17], v[100:101], 1, v[14:15]
	global_load_dwordx4 v[10:13], v[0:1], off offset:1024
	v_lshl_add_u64 v[0:1], v[102:103], 1, v[14:15]
	s_addc_u32 s17, s63, 0
	s_lshl_b32 s98, s98, 2
	s_add_u32 s16, s16, s98
	s_addc_u32 s17, s17, 0
	v_lshlrev_b32_e32 v14, 2, v114
	v_mov_b32_e32 v15, v113
	s_movk_i32 s15, 0x90
	v_lshl_add_u64 v[104:105], s[16:17], 0, v[14:15]
	v_mad_u64_u32 v[106:107], s[16:17], v145, s15, v[112:113]
	v_mul_lo_u32 v5, v100, s15
	v_lshlrev_b32_e32 v14, 1, v135
	v_or_b32_e32 v107, v5, v14
	v_mad_u64_u32 v[108:109], s[16:17], v146, s15, v[112:113]
	v_mul_lo_u32 v5, v102, s15
	s_movk_i32 s44, 0x90
	v_or_b32_e32 v109, v5, v14
	v_cmp_gt_i32_e64 s[40:41], 64, v3
	v_lshlrev_b32_e32 v147, 2, v3
	v_readlane_b32 s49, v165, 27
	v_readlane_b32 s50, v165, 28
	v_readlane_b32 s51, v165, 29
	v_readlane_b32 s52, v165, 30
	v_readlane_b32 s53, v165, 31
	v_readlane_b32 s54, v165, 32
	v_readlane_b32 s55, v165, 33
	v_readlane_b32 s56, v165, 34
	v_readlane_b32 s57, v165, 35
	v_readlane_b32 s58, v165, 36
	v_readlane_b32 s59, v165, 37
	v_readlane_b32 s60, v165, 38
	v_readlane_b32 s61, v165, 39
	s_waitcnt vmcnt(1)
	ds_write_b128 v106, v[6:9]
	global_load_dwordx4 v[6:9], v[16:17], off offset:2048
	s_waitcnt vmcnt(0)
	ds_write_b16 v107, v6 offset:9216
	ds_write_b16_d16_hi v107, v6 offset:9360
	ds_write_b16 v107, v7 offset:9504
	ds_write_b16_d16_hi v107, v7 offset:9648
	ds_write_b16 v107, v8 offset:9792
	ds_write_b16_d16_hi v107, v8 offset:9936
	ds_write_b16 v107, v9 offset:10080
	ds_write_b16_d16_hi v107, v9 offset:10224
	global_load_dwordx4 v[6:9], v[0:1], off offset:2048
	ds_write_b128 v108, v[10:13]
	s_waitcnt vmcnt(0)
	ds_write_b16 v109, v6 offset:9216
	ds_write_b16_d16_hi v109, v6 offset:9360
	ds_write_b16 v109, v7 offset:9504
	ds_write_b16_d16_hi v109, v7 offset:9648
	ds_write_b16 v109, v8 offset:9792
	ds_write_b16_d16_hi v109, v8 offset:9936
	ds_write_b16 v109, v9 offset:10080
	ds_write_b16_d16_hi v109, v9 offset:10224
	s_and_saveexec_b64 s[24:25], s[40:41]
	s_cbranch_execz .LBB0_109
	v_mov_b32_e32 v0, s99
	v_lshlrev_b32_e32 v0, 2, v0
	v_mov_b32_e32 v1, 0
	v_lshl_add_u64 v[0:1], v[104:105], 0, v[0:1]
	global_load_dword v0, v[0:1], off
	s_waitcnt vmcnt(0)
	ds_write_b32 v147, v0 offset:18432
; __device__ void attn_item(const Params& p, int s_idx, char* smem) {
;     ...
;     auto gload = [&](int kt, KV& st) {
; #pragma unroll
;         for (int i = 0; i < 2; ++i) {
;             const int c = tid + 256 * i, key = c >> 3, dc = c & 7;
;             const bf16_t* src = projb + (size_t)(kt * 64 + key) * NIN + h * 64 + dc * 8;
;             st.rk[i] = *(const u32x4*)(src + 512);
;             const int keyv = c & 63, dcv = c >> 6;
;             st.rv[i] = *(const u32x4*)(projb + (size_t)(kt * 64 + keyv) * NIN + 1024 + h * 64 + dcv * 8);
;         }
;         st.rkb = p.kb[(size_t)bh * S + kt * 64 + (tid & 63)];
;     };
.LBB0_109:
	s_or_b64 exec, exec, s[24:25]
	v_and_b32_e32 v0, 19, v3
	v_lshlrev_b32_e32 v1, 1, v2
	v_lshrrev_b32_e32 v3, 1, v3
	v_and_b32_e32 v1, 8, v1
	v_and_b32_e32 v3, 4, v3
	v_lshlrev_b32_e32 v141, 3, v4
	s_lshl_b32 s14, s14, 1
	v_or3_b32 v0, v3, v0, v1
	s_mul_i32 s98, s99, 0x1410
	s_sub_u32 s34, s34, s98
	s_subb_u32 s35, s35, 0
	s_add_u32 s34, s34, s22
	v_mul_u32_u24_e32 v0, 0x48, v0
	v_lshlrev_b32_e32 v1, 1, v141
	v_mul_u32_u24_e32 v148, 0x48, v2
	v_mov_b32_e32 v14, v113
	v_mov_b32_e32 v15, v113
	s_addc_u32 s35, s35, 0
	v_lshl_add_u32 v150, v0, 1, v1
	v_lshl_add_u32 v152, v148, 1, v1
	s_mov_b32 s20, 0
	v_mov_b32_e32 v0, v113
	v_mov_b32_e32 v1, v113
	v_mov_b32_e32 v2, v113
	v_mov_b32_e32 v3, v113
	v_mov_b32_e32 v4, v113
	v_mov_b32_e32 v5, v113
	v_mov_b32_e32 v6, v113
	v_mov_b32_e32 v7, v113
	v_mov_b32_e32 v8, v113
	v_mov_b32_e32 v9, v113
	v_mov_b32_e32 v10, v113
	v_mov_b32_e32 v11, v113
	v_mov_b32_e32 v12, v113
	v_mov_b32_e32 v13, v113
	v_mov_b64_e32 v[30:31], v[14:15]
	v_ashrrev_i32_e32 v149, 6, v144
	v_lshl_add_u64 v[110:111], s[34:35], 0, v[112:113]
	v_lshlrev_b32_e32 v151, 2, v141
	s_or_b32 s15, s14, 1
	s_sub_i32 s14, s14, s32
	s_sub_i32 s15, s15, s32
	v_mov_b32_e32 v97, v98
	v_mov_b32_e32 v99, v98
	v_add_u32_e32 v153, 0xffffffc0, v146
	v_add_u32_e32 v154, 0xffffffc0, v135
	v_add_u32_e32 v155, 0xffffffc0, v145
	v_mov_b32_e32 v157, 0xff800000
	v_mov_b32_e32 v156, 0
	s_mov_b32 s16, s15
	s_lshl_b32 s20, s15, 6
	v_add_u32_e32 v127, s20, v155
	v_add_u32_e32 v128, s20, v153
	v_add_u32_e32 v129, s20, v154
	v_mul_lo_u32 v127, v127, s29
	v_mul_lo_u32 v128, v128, s29
	v_mul_lo_u32 v129, v129, s29
	v_add_u32_e32 v127, v127, v112
	v_add_u32_e32 v128, v128, v112
	v_lshl_add_u32 v131, v102, 1, v129
	v_lshl_add_u32 v129, v100, 1, v129
	v_mov_b64_e32 v[28:29], v[12:13]
	v_mov_b64_e32 v[26:27], v[10:11]
	v_mov_b64_e32 v[24:25], v[8:9]
	v_mov_b64_e32 v[22:23], v[6:7]
	v_mov_b64_e32 v[20:21], v[4:5]
	v_mov_b64_e32 v[18:19], v[2:3]
	v_mov_b64_e32 v[16:17], v[0:1]
	s_waitcnt lgkmcnt(0)
	s_barrier
; __device__ void attn_item(const Params& p, int s_idx, char* smem) {
;     ...
;     auto gload = [&](int kt, KV& st) {
; #pragma unroll
;         for (int i = 0; i < 2; ++i) {
;             const int c = tid + 256 * i, key = c >> 3, dc = c & 7;
;             const bf16_t* src = projb + (size_t)(kt * 64 + key) * NIN + h * 64 + dc * 8;
;             st.rk[i] = *(const u32x4*)(src + 512);
;             const int keyv = c & 63, dcv = c >> 6;
;             st.rv[i] = *(const u32x4*)(projb + (size_t)(kt * 64 + keyv) * NIN + 1024 + h * 64 + dcv * 8);
;         }
;         st.rkb = p.kb[(size_t)bh * S + kt * 64 + (tid & 63)];
;     ...
;     auto compute = [&](int kt, int buf) {
;         if (kt <= wave_last) {
;             const bf16_t* sK = (const bf16_t*)(smem + buf * ATT_BUF); const bf16_t* sVt = sK + 64 * 72; const float* sKb = (const float*)(smem + buf * ATT_BUF + 18432);
;             f32x16 S0, S1;
; #pragma unroll
;             for (int i = 0; i < 16; ++i) { S0[i] = 0.f; S1[i] = 0.f; }
; #pragma unroll
;             for (int kk = 0; kk < 4; ++kk) {
;                 const bf16x8 k0 = *(const bf16x8*)(sK + pr * 72 + kk * 16 + hh * 8);
;                 const bf16x8 k1 = *(const bf16x8*)(sK + (32 + pr) * 72 + kk * 16 + hh * 8);
;                 S0 = __builtin_amdgcn_mfma_f32_32x32x16_bf16(k0, qf[kk], S0, 0, 0, 0);
;                 S1 = __builtin_amdgcn_mfma_f32_32x32x16_bf16(k1, qf[kk], S1, 0, 0, 0);
;             }
;             float sv[32];
; #pragma unroll
;             for (int g = 0; g < 4; ++g) {
;                 const int kbase = (g >> 1) * 32 + (g & 1) * 16 + 8 * hh;
;                 const float4 b0 = *(const float4*)(sKb + kbase), b1 = *(const float4*)(sKb + kbase + 4);
;                 const int o = (g & 1) * 8;
;                 if (g >> 1) {
;                     sv[g * 8 + 0] = S1[o + 0] * sc + b0.x; sv[g * 8 + 1] = S1[o + 1] * sc + b0.y; sv[g * 8 + 2] = S1[o + 2] * sc + b0.z; sv[g * 8 + 3] = S1[o + 3] * sc + b0.w;
;                     sv[g * 8 + 4] = S1[o + 4] * sc + b1.x; sv[g * 8 + 5] = S1[o + 5] * sc + b1.y; sv[g * 8 + 6] = S1[o + 6] * sc + b1.z; sv[g * 8 + 7] = S1[o + 7] * sc + b1.w;
;                 } else {
;                     sv[g * 8 + 0] = S0[o + 0] * sc + b0.x; sv[g * 8 + 1] = S0[o + 1] * sc + b0.y; sv[g * 8 + 2] = S0[o + 2] * sc + b0.z; sv[g * 8 + 3] = S0[o + 3] * sc + b0.w;
.LBB0_110:
	s_cmp_gt_u32 s16, 1
	s_cselect_b32 s32, 0xfffafc00, 0
	global_load_dwordx4 v[92:95], v127, s[34:35] offset:1024
	global_load_dwordx4 v[84:87], v129, s[34:35] offset:2048
	global_load_dwordx4 v[88:91], v128, s[34:35] offset:1024
	global_load_dwordx4 v[80:83], v131, s[34:35] offset:2048
	v_add_u32_e32 v127, s32, v127
	v_add_u32_e32 v129, s32, v129
	v_add_u32_e32 v128, s32, v128
	v_add_u32_e32 v131, s32, v131
	v_lshl_add_u64 v[32:33], s[20:21], 2, v[104:105]
	global_load_dword v158, v[32:33], off offset:-256
	v_cmp_le_i32_e32 vcc, s16, v149
	s_and_saveexec_b64 s[36:37], vcc
	s_cbranch_execz .LBB0_114
	ds_read_b128 v[32:35], v150 offset:4608
	ds_read_b128 v[36:39], v150
	ds_read_b128 v[116:119], v150 offset:32
	ds_read_b128 v[120:123], v150 offset:4640
	s_add_i32 s17, s20, 63
	v_cmp_gt_i32_e32 vcc, s17, v144
	s_waitcnt lgkmcnt(2)
	v_mfma_f32_32x32x16_bf16 v[48:63], v[36:39], v[64:67], 0
	v_mfma_f32_32x32x16_bf16 v[32:47], v[32:35], v[64:67], 0
	s_waitcnt lgkmcnt(1)
	v_mfma_f32_32x32x16_bf16 v[48:63], v[116:119], v[68:71], v[48:63]
	s_waitcnt lgkmcnt(0)
	v_mfma_f32_32x32x16_bf16 v[32:47], v[120:123], v[68:71], v[32:47]
	ds_read_b128 v[116:119], v150 offset:64
	ds_read_b128 v[120:123], v150 offset:4672
	s_waitcnt lgkmcnt(1)
	v_mfma_f32_32x32x16_bf16 v[48:63], v[116:119], v[72:75], v[48:63]
	s_waitcnt lgkmcnt(0)
	v_mfma_f32_32x32x16_bf16 v[32:47], v[120:123], v[72:75], v[32:47]
	ds_read_b128 v[116:119], v150 offset:96
	ds_read_b128 v[120:123], v150 offset:4704
	s_waitcnt lgkmcnt(1)
	v_mfma_f32_32x32x16_bf16 v[48:63], v[116:119], v[76:79], v[48:63]
	ds_read_b128 v[116:119], v151 offset:18432
	ds_read_b128 v[160:163], v151 offset:18448
	s_waitcnt lgkmcnt(2)
	v_mfma_f32_32x32x16_bf16 v[32:47], v[120:123], v[76:79], v[32:47]
	s_waitcnt lgkmcnt(1)
	s_nop 6
	v_fma_f32 v122, v48, s30, v116
	v_fma_f32 v123, v49, s30, v117
	v_fma_f32 v120, v50, s30, v118
	v_fma_f32 v121, v51, s30, v119
	ds_read_b128 v[48:51], v151 offset:18496
	s_waitcnt lgkmcnt(1)
	v_pk_fma_f32 v[118:119], v[52:53], s[30:31], v[160:161] op_sel_hi:[1,0,1]
	v_pk_fma_f32 v[54:55], v[54:55], s[30:31], v[162:163] op_sel_hi:[1,0,1]
	ds_read_b128 v[160:163], v151 offset:18560
	s_waitcnt lgkmcnt(1)
	v_pk_fma_f32 v[116:117], v[56:57], s[30:31], v[48:49] op_sel_hi:[1,0,1]
	v_pk_fma_f32 v[50:51], v[58:59], s[30:31], v[50:51] op_sel_hi:[1,0,1]
	ds_read_b128 v[56:59], v151 offset:18512
	s_waitcnt lgkmcnt(1)
	v_pk_fma_f32 v[52:53], v[34:35], s[30:31], v[162:163] op_sel_hi:[1,0,1]
	s_waitcnt lgkmcnt(0)
	v_pk_fma_f32 v[124:125], v[60:61], s[30:31], v[56:57] op_sel_hi:[1,0,1]
	v_pk_fma_f32 v[60:61], v[62:63], s[30:31], v[58:59] op_sel_hi:[1,0,1]
	v_pk_fma_f32 v[58:59], v[32:33], s[30:31], v[160:161] op_sel_hi:[1,0,1]
	ds_read_b128 v[32:35], v151 offset:18576
	s_waitcnt lgkmcnt(0)
	v_pk_fma_f32 v[56:57], v[36:37], s[30:31], v[32:33] op_sel_hi:[1,0,1]
	v_pk_fma_f32 v[48:49], v[38:39], s[30:31], v[34:35] op_sel_hi:[1,0,1]
	ds_read_b128 v[32:35], v151 offset:18624
	s_waitcnt lgkmcnt(0)
	v_pk_fma_f32 v[38:39], v[40:41], s[30:31], v[32:33] op_sel_hi:[1,0,1]
	v_pk_fma_f32 v[34:35], v[42:43], s[30:31], v[34:35] op_sel_hi:[1,0,1]
	ds_read_b128 v[40:43], v151 offset:18640
	s_waitcnt lgkmcnt(0)
	v_pk_fma_f32 v[36:37], v[44:45], s[30:31], v[40:41] op_sel_hi:[1,0,1]
	v_pk_fma_f32 v[32:33], v[46:47], s[30:31], v[42:43] op_sel_hi:[1,0,1]
	s_and_saveexec_b64 s[42:43], vcc
	s_cbranch_execz .LBB0_113
	v_add_u32_e32 v40, s20, v141
	v_cmp_ge_i32_e32 vcc, v99, v40
	v_or_b32_e32 v41, 3, v40
	v_or_b32_e32 v42, 2, v40
	v_cndmask_b32_e32 v122, v139, v122, vcc
	v_cmp_lt_i32_e32 vcc, v40, v99
	s_nop 1
	v_cndmask_b32_e32 v123, v139, v123, vcc
	v_cmp_le_i32_e32 vcc, v41, v97
	v_or_b32_e32 v41, 5, v40
	s_nop 0
	v_cndmask_b32_e32 v121, v139, v121, vcc
	v_cmp_le_i32_e32 vcc, v42, v98
	v_or_b32_e32 v42, 4, v40
	s_nop 0
	v_cndmask_b32_e32 v120, v139, v120, vcc
	v_cmp_le_i32_e32 vcc, v41, v97
	v_or_b32_e32 v41, 7, v40
	s_nop 0
	v_cndmask_b32_e32 v119, v139, v119, vcc
	v_cmp_le_i32_e32 vcc, v42, v98
	v_or_b32_e32 v42, 6, v40
	s_nop 0
	v_cndmask_b32_e32 v118, v139, v118, vcc
	v_cmp_le_i32_e32 vcc, v41, v97
	v_or_b32_e32 v41, 17, v40
	s_nop 0
	v_cndmask_b32_e32 v55, v139, v55, vcc
	v_cmp_le_i32_e32 vcc, v42, v98
	v_or_b32_e32 v42, 16, v40
	s_nop 0
	v_cndmask_b32_e32 v54, v139, v54, vcc
	v_cmp_le_i32_e32 vcc, v41, v97
	v_or_b32_e32 v41, 19, v40
	s_nop 0
	v_cndmask_b32_e32 v117, v139, v117, vcc
	v_cmp_le_i32_e32 vcc, v42, v98
	v_or_b32_e32 v42, 18, v40
	s_nop 0
	v_cndmask_b32_e32 v116, v139, v116, vcc
	v_cmp_le_i32_e32 vcc, v41, v97
	v_or_b32_e32 v41, 21, v40
	s_nop 0
	v_cndmask_b32_e32 v51, v139, v51, vcc
	v_cmp_le_i32_e32 vcc, v42, v98
	v_or_b32_e32 v42, 20, v40
	s_nop 0
	v_cndmask_b32_e32 v50, v139, v50, vcc
	v_cmp_le_i32_e32 vcc, v41, v97
	v_or_b32_e32 v41, 23, v40
	s_nop 0
	v_cndmask_b32_e32 v125, v139, v125, vcc
	v_cmp_le_i32_e32 vcc, v42, v98
	v_or_b32_e32 v42, 22, v40
	s_nop 0
	v_cndmask_b32_e32 v124, v139, v124, vcc
	v_cmp_le_i32_e32 vcc, v41, v97
	v_or_b32_e32 v41, 33, v40
	s_nop 0
	v_cndmask_b32_e32 v61, v139, v61, vcc
	v_cmp_le_i32_e32 vcc, v42, v98
	v_or_b32_e32 v42, 32, v40
	s_nop 0
	v_cndmask_b32_e32 v60, v139, v60, vcc
	v_cmp_le_i32_e32 vcc, v41, v97
	v_or_b32_e32 v41, 35, v40
	s_nop 0
	v_cndmask_b32_e32 v59, v139, v59, vcc
	v_cmp_le_i32_e32 vcc, v42, v98
	v_or_b32_e32 v42, 34, v40
	s_nop 0
	v_cndmask_b32_e32 v58, v139, v58, vcc
	v_cmp_le_i32_e32 vcc, v41, v97
	v_or_b32_e32 v41, 37, v40
	s_nop 0
	v_cndmask_b32_e32 v53, v139, v53, vcc
	v_cmp_le_i32_e32 vcc, v42, v98
	v_or_b32_e32 v42, 36, v40
	s_nop 0
	v_cndmask_b32_e32 v52, v139, v52, vcc
	v_cmp_le_i32_e32 vcc, v41, v97
	v_or_b32_e32 v41, 39, v40
	s_nop 0
	v_cndmask_b32_e32 v57, v139, v57, vcc
	v_cmp_le_i32_e32 vcc, v42, v98
	v_or_b32_e32 v42, 38, v40
	s_nop 0
	v_cndmask_b32_e32 v56, v139, v56, vcc
	v_cmp_le_i32_e32 vcc, v41, v97
	v_or_b32_e32 v41, 49, v40
	s_nop 0
	v_cndmask_b32_e32 v49, v139, v49, vcc
	v_cmp_le_i32_e32 vcc, v42, v98
	v_or_b32_e32 v42, 48, v40
	s_nop 0
	v_cndmask_b32_e32 v48, v139, v48, vcc
	v_cmp_le_i32_e32 vcc, v41, v97
	v_or_b32_e32 v41, 51, v40
	s_nop 0
	v_cndmask_b32_e32 v39, v139, v39, vcc
	v_cmp_le_i32_e32 vcc, v42, v98
	v_or_b32_e32 v42, 50, v40
	s_nop 0
	v_cndmask_b32_e32 v38, v139, v38, vcc
	v_cmp_le_i32_e32 vcc, v41, v97
	v_or_b32_e32 v41, 53, v40
	s_nop 0
	v_cndmask_b32_e32 v35, v139, v35, vcc
	v_cmp_le_i32_e32 vcc, v42, v98
	v_or_b32_e32 v42, 52, v40
	s_nop 0
	v_cndmask_b32_e32 v34, v139, v34, vcc
	v_cmp_le_i32_e32 vcc, v41, v97
	v_or_b32_e32 v41, 55, v40
	v_or_b32_e32 v40, 54, v40
	v_cndmask_b32_e32 v37, v139, v37, vcc
	v_cmp_le_i32_e32 vcc, v42, v98
	s_nop 1
	v_cndmask_b32_e32 v36, v139, v36, vcc
	v_cmp_le_i32_e32 vcc, v41, v97
	s_nop 1
	v_cndmask_b32_e32 v33, v139, v33, vcc
	v_cmp_le_i32_e32 vcc, v40, v98
	s_nop 1
	v_cndmask_b32_e32 v32, v139, v32, vcc

; __device__ void attn_item(const Params& p, int s_idx, char* smem) {
;     ...
;     auto gload = [&](int kt, KV& st) {
; #pragma unroll
;         for (int i = 0; i < 2; ++i) {
;             const int c = tid + 256 * i, key = c >> 3, dc = c & 7;
;             const bf16_t* src = projb + (size_t)(kt * 64 + key) * NIN + h * 64 + dc * 8;
;             st.rk[i] = *(const u32x4*)(src + 512);
;             const int keyv = c & 63, dcv = c >> 6;
;             st.rv[i] = *(const u32x4*)(projb + (size_t)(kt * 64 + keyv) * NIN + 1024 + h * 64 + dcv * 8);
;         }
;         st.rkb = p.kb[(size_t)bh * S + kt * 64 + (tid & 63)];
;     ...
;         gload(kt + 1, sa);
;         compute(kt, 0);
;         sstore(1, sa);
;         __syncthreads();
;         gload(min(kt + 2, nkt - 1), sa);
;         compute(kt + 1, 1);
.LBB0_116:
	s_or_b64 exec, exec, s[24:25]
	s_add_i32 s17, s16, -2
	s_max_i32 s18, s17, 0
	s_lshl_b32 s18, s18, 6
	s_waitcnt lgkmcnt(0)
	s_barrier
	global_load_dwordx4 v[92:95], v127, s[34:35] offset:1024
	global_load_dwordx4 v[84:87], v129, s[34:35] offset:2048
	s_mov_b32 s19, s21
	global_load_dwordx4 v[88:91], v128, s[34:35] offset:1024
	global_load_dwordx4 v[80:83], v131, s[34:35] offset:2048
	v_add_u32_e32 v127, s32, v127
	v_add_u32_e32 v129, s32, v129
	v_add_u32_e32 v128, s32, v128
	v_add_u32_e32 v131, s32, v131
	v_lshl_add_u64 v[32:33], s[18:19], 2, v[104:105]
	global_load_dword v158, v[32:33], off
	v_cmp_lt_i32_e32 vcc, s17, v149
	s_and_saveexec_b64 s[36:37], vcc
	s_cbranch_execz .LBB0_120
	ds_read_b128 v[32:35], v150 offset:23296
	ds_read_b128 v[36:39], v150 offset:18688
	ds_read_b128 v[116:119], v150 offset:18720
	ds_read_b128 v[120:123], v150 offset:23328
	s_add_i32 s18, s20, -1
	v_cmp_gt_i32_e32 vcc, s18, v144
	s_waitcnt lgkmcnt(2)
	v_mfma_f32_32x32x16_bf16 v[48:63], v[36:39], v[64:67], 0
	v_mfma_f32_32x32x16_bf16 v[32:47], v[32:35], v[64:67], 0
	s_waitcnt lgkmcnt(1)
	v_mfma_f32_32x32x16_bf16 v[48:63], v[116:119], v[68:71], v[48:63]
	s_waitcnt lgkmcnt(0)
	v_mfma_f32_32x32x16_bf16 v[32:47], v[120:123], v[68:71], v[32:47]
	ds_read_b128 v[116:119], v150 offset:18752
	ds_read_b128 v[120:123], v150 offset:23360
	s_waitcnt lgkmcnt(1)
	v_mfma_f32_32x32x16_bf16 v[48:63], v[116:119], v[72:75], v[48:63]
	s_waitcnt lgkmcnt(0)
	v_mfma_f32_32x32x16_bf16 v[32:47], v[120:123], v[72:75], v[32:47]
	ds_read_b128 v[116:119], v150 offset:18784
	ds_read_b128 v[120:123], v150 offset:23392
	s_waitcnt lgkmcnt(1)
	v_mfma_f32_32x32x16_bf16 v[48:63], v[116:119], v[76:79], v[48:63]
	ds_read_b128 v[116:119], v151 offset:37120
	ds_read_b128 v[160:163], v151 offset:37136
	s_waitcnt lgkmcnt(2)
	v_mfma_f32_32x32x16_bf16 v[32:47], v[120:123], v[76:79], v[32:47]
	s_waitcnt lgkmcnt(1)
	s_nop 6
	v_fma_f32 v122, v48, s30, v116
	v_fma_f32 v123, v49, s30, v117
	v_fma_f32 v120, v50, s30, v118
	v_fma_f32 v121, v51, s30, v119
	ds_read_b128 v[48:51], v151 offset:37184
	s_waitcnt lgkmcnt(1)
	v_pk_fma_f32 v[118:119], v[52:53], s[30:31], v[160:161] op_sel_hi:[1,0,1]
	v_pk_fma_f32 v[54:55], v[54:55], s[30:31], v[162:163] op_sel_hi:[1,0,1]
	ds_read_b128 v[160:163], v151 offset:37248
	s_waitcnt lgkmcnt(1)
	v_pk_fma_f32 v[116:117], v[56:57], s[30:31], v[48:49] op_sel_hi:[1,0,1]
	v_pk_fma_f32 v[50:51], v[58:59], s[30:31], v[50:51] op_sel_hi:[1,0,1]
	ds_read_b128 v[56:59], v151 offset:37200
	s_waitcnt lgkmcnt(1)
	v_pk_fma_f32 v[52:53], v[34:35], s[30:31], v[162:163] op_sel_hi:[1,0,1]
	s_waitcnt lgkmcnt(0)
	v_pk_fma_f32 v[124:125], v[60:61], s[30:31], v[56:57] op_sel_hi:[1,0,1]
	v_pk_fma_f32 v[60:61], v[62:63], s[30:31], v[58:59] op_sel_hi:[1,0,1]
	v_pk_fma_f32 v[58:59], v[32:33], s[30:31], v[160:161] op_sel_hi:[1,0,1]
	ds_read_b128 v[32:35], v151 offset:37264
	s_waitcnt lgkmcnt(0)
	v_pk_fma_f32 v[56:57], v[36:37], s[30:31], v[32:33] op_sel_hi:[1,0,1]
	v_pk_fma_f32 v[48:49], v[38:39], s[30:31], v[34:35] op_sel_hi:[1,0,1]
	ds_read_b128 v[32:35], v151 offset:37312
	s_waitcnt lgkmcnt(0)
	v_pk_fma_f32 v[38:39], v[40:41], s[30:31], v[32:33] op_sel_hi:[1,0,1]
	v_pk_fma_f32 v[34:35], v[42:43], s[30:31], v[34:35] op_sel_hi:[1,0,1]
	ds_read_b128 v[40:43], v151 offset:37328
	s_waitcnt lgkmcnt(0)
	v_pk_fma_f32 v[36:37], v[44:45], s[30:31], v[40:41] op_sel_hi:[1,0,1]
	v_pk_fma_f32 v[32:33], v[46:47], s[30:31], v[42:43] op_sel_hi:[1,0,1]
	s_and_saveexec_b64 s[42:43], vcc
	s_cbranch_execz .LBB0_119
	s_add_i32 s19, s20, 0xffffffc0
	v_add_u32_e32 v40, s19, v141
	v_cmp_ge_i32_e32 vcc, v99, v40
	v_or_b32_e32 v41, 3, v40
	v_or_b32_e32 v42, 2, v40
	v_cndmask_b32_e32 v122, v139, v122, vcc
	v_cmp_lt_i32_e32 vcc, v40, v99
	s_nop 1
	v_cndmask_b32_e32 v123, v139, v123, vcc
	v_cmp_le_i32_e32 vcc, v41, v97
	v_or_b32_e32 v41, 5, v40
	s_nop 0
	v_cndmask_b32_e32 v121, v139, v121, vcc
	v_cmp_le_i32_e32 vcc, v42, v98
	v_or_b32_e32 v42, 4, v40
	s_nop 0
	v_cndmask_b32_e32 v120, v139, v120, vcc
	v_cmp_le_i32_e32 vcc, v41, v97
	v_or_b32_e32 v41, 7, v40
	s_nop 0
	v_cndmask_b32_e32 v119, v139, v119, vcc
	v_cmp_le_i32_e32 vcc, v42, v98
	v_or_b32_e32 v42, 6, v40
	s_nop 0
	v_cndmask_b32_e32 v118, v139, v118, vcc
	v_cmp_le_i32_e32 vcc, v41, v97
	v_or_b32_e32 v41, 17, v40
	s_nop 0
	v_cndmask_b32_e32 v55, v139, v55, vcc
	v_cmp_le_i32_e32 vcc, v42, v98
	v_or_b32_e32 v42, 16, v40
	s_nop 0
	v_cndmask_b32_e32 v54, v139, v54, vcc
	v_cmp_le_i32_e32 vcc, v41, v97
	v_or_b32_e32 v41, 19, v40
	s_nop 0
	v_cndmask_b32_e32 v117, v139, v117, vcc
	v_cmp_le_i32_e32 vcc, v42, v98
	v_or_b32_e32 v42, 18, v40
	s_nop 0
	v_cndmask_b32_e32 v116, v139, v116, vcc
	v_cmp_le_i32_e32 vcc, v41, v97
	v_or_b32_e32 v41, 21, v40
	s_nop 0
	v_cndmask_b32_e32 v51, v139, v51, vcc
	v_cmp_le_i32_e32 vcc, v42, v98
	v_or_b32_e32 v42, 20, v40
	s_nop 0
	v_cndmask_b32_e32 v50, v139, v50, vcc
	v_cmp_le_i32_e32 vcc, v41, v97
	v_or_b32_e32 v41, 23, v40
	s_nop 0
	v_cndmask_b32_e32 v125, v139, v125, vcc
	v_cmp_le_i32_e32 vcc, v42, v98
	v_or_b32_e32 v42, 22, v40
	s_nop 0
	v_cndmask_b32_e32 v124, v139, v124, vcc
	v_cmp_le_i32_e32 vcc, v41, v97
	v_or_b32_e32 v41, 33, v40
	s_nop 0
	v_cndmask_b32_e32 v61, v139, v61, vcc
	v_cmp_le_i32_e32 vcc, v42, v98
	v_or_b32_e32 v42, 32, v40
	s_nop 0
	v_cndmask_b32_e32 v60, v139, v60, vcc
	v_cmp_le_i32_e32 vcc, v41, v97
	v_or_b32_e32 v41, 35, v40
	s_nop 0
	v_cndmask_b32_e32 v59, v139, v59, vcc
	v_cmp_le_i32_e32 vcc, v42, v98
	v_or_b32_e32 v42, 34, v40
	s_nop 0
	v_cndmask_b32_e32 v58, v139, v58, vcc
	v_cmp_le_i32_e32 vcc, v41, v97
	v_or_b32_e32 v41, 37, v40
	s_nop 0
	v_cndmask_b32_e32 v53, v139, v53, vcc
	v_cmp_le_i32_e32 vcc, v42, v98
	v_or_b32_e32 v42, 36, v40
	s_nop 0
	v_cndmask_b32_e32 v52, v139, v52, vcc
	v_cmp_le_i32_e32 vcc, v41, v97
	v_or_b32_e32 v41, 39, v40
	s_nop 0
	v_cndmask_b32_e32 v57, v139, v57, vcc
	v_cmp_le_i32_e32 vcc, v42, v98
	v_or_b32_e32 v42, 38, v40
	s_nop 0
	v_cndmask_b32_e32 v56, v139, v56, vcc
	v_cmp_le_i32_e32 vcc, v41, v97
	v_or_b32_e32 v41, 49, v40
	s_nop 0
	v_cndmask_b32_e32 v49, v139, v49, vcc
	v_cmp_le_i32_e32 vcc, v42, v98
	v_or_b32_e32 v42, 48, v40
	s_nop 0
	v_cndmask_b32_e32 v48, v139, v48, vcc
	v_cmp_le_i32_e32 vcc, v41, v97
	v_or_b32_e32 v41, 51, v40
	s_nop 0
	v_cndmask_b32_e32 v39, v139, v39, vcc
	v_cmp_le_i32_e32 vcc, v42, v98
	v_or_b32_e32 v42, 50, v40
	s_nop 0
	v_cndmask_b32_e32 v38, v139, v38, vcc
	v_cmp_le_i32_e32 vcc, v41, v97
	v_or_b32_e32 v41, 53, v40
	s_nop 0
	v_cndmask_b32_e32 v35, v139, v35, vcc
	v_cmp_le_i32_e32 vcc, v42, v98
	v_or_b32_e32 v42, 52, v40
	s_nop 0
	v_cndmask_b32_e32 v34, v139, v34, vcc
	v_cmp_le_i32_e32 vcc, v41, v97
	v_or_b32_e32 v41, 55, v40
	v_or_b32_e32 v40, 54, v40
	v_cndmask_b32_e32 v37, v139, v37, vcc
	v_cmp_le_i32_e32 vcc, v42, v98
	s_nop 1
	v_cndmask_b32_e32 v36, v139, v36, vcc
	v_cmp_le_i32_e32 vcc, v41, v97
	s_nop 1
	v_cndmask_b32_e32 v33, v139, v33, vcc
	v_cmp_le_i32_e32 vcc, v40, v98
	s_nop 1
	v_cndmask_b32_e32 v32, v139, v32, vcc
